# back-edge rotation (7.11) on mixer-A tile loop: loop head is the barrier, exit test and slot select moved before it
# baseline (speedup 1.0000x reference)
.Lattn_prio_skip_a:
	s_mov_b32 s7, 0
.Lattn_head_a:
	s_barrier
.LBB0_407:
	v_mbcnt_lo_u32_b32 v128, -1, 0
	v_mbcnt_hi_u32_b32 v128, -1, v128
	s_add_i32 s7, s7, 0
	v_bfe_u32 v129, v128, 2, 2
	v_lshrrev_b32_e32 v130, 3, v128
	v_bfe_u32 v132, v128, 1, 1
	v_and_or_b32 v131, v130, s64, v129
	v_and_or_b32 v130, v130, 2, v132
	v_lshlrev_b32_e32 v128, 3, v128
	v_lshlrev_b32_e32 v131, 8, v131
	v_lshlrev_b32_e32 v130, 4, v130
	v_and_b32_e32 v128, 8, v128
	v_or3_b32 v160, v130, v131, v128
	v_lshlrev_b32_e32 v162, 6, v129
	v_mbcnt_lo_u32_b32 v128, -1, 0
	v_mbcnt_hi_u32_b32 v128, -1, v128
	v_or_b32_e32 v163, v160, v162
	v_ashrrev_i32_e32 v129, 5, v128
	v_lshlrev_b32_e32 v130, 7, v128
	v_lshrrev_b32_e32 v133, 1, v128
	v_and_b32_e32 v132, 0xf80, v130
	v_bitop3_b32 v128, v133, v129, 7 bitop3:0x6c
	v_lshl_add_u32 v134, v128, 4, v132
	v_add_u32_e32 v128, 2, v129
	v_bitop3_b32 v128, v128, v133, 7 bitop3:0x78
	v_lshl_add_u32 v136, v128, 4, v132
	v_add_u32_e32 v128, 4, v129
	v_bitop3_b32 v128, v128, v133, 7 bitop3:0x78
	v_add_u32_e32 v207, s7, v134
	v_lshl_add_u32 v168, v128, 4, v132
	v_add_u32_e32 v135, 6, v129
	ds_read_b128 v[128:131], v207
	v_bitop3_b32 v133, v135, v133, 7 bitop3:0x78
	v_add_u32_e32 v224, s48, v134
	v_add_u32_e32 v225, s7, v136
	v_lshl_add_u32 v169, v133, 4, v132
	ds_read_b128 v[132:135], v224
	v_add_u32_e32 v226, s48, v136
	ds_read_b128 v[136:139], v225
	ds_read_b128 v[140:143], v226
	v_bitop3_b32 v203, v160, s37, v162 bitop3:0x36
	v_bitop3_b32 v206, v160, s41, v162 bitop3:0x36
	s_waitcnt lgkmcnt(2)
	v_mfma_f32_32x32x16_bf16 v[144:159], v[128:131], v[132:135], 0
	v_add_u32_e32 v227, s7, v168
	v_add_u32_e32 v228, s48, v168
	ds_read_b128 v[128:131], v227
	ds_read_b128 v[132:135], v228
	s_waitcnt lgkmcnt(2)
	v_mfma_f32_32x32x16_bf16 v[144:159], v[136:139], v[140:143], v[144:159]
	v_add_u32_e32 v230, s7, v169
	v_add_u32_e32 v232, s48, v169
	ds_read_b128 v[136:139], v230
	ds_read_b128 v[140:143], v232
	s_waitcnt lgkmcnt(2)
	v_mfma_f32_32x32x16_bf16 v[144:159], v[128:131], v[132:135], v[144:159]
	ds_read_b128 v[128:131], v207 offset:8192
	ds_read_b128 v[132:135], v224 offset:4096
	s_waitcnt lgkmcnt(2)
	v_mfma_f32_32x32x16_bf16 v[144:159], v[136:139], v[140:143], v[144:159]
	ds_read_b128 v[178:181], v225 offset:8192
	ds_read_b128 v[182:185], v226 offset:4096
	s_waitcnt lgkmcnt(2)
	v_mfma_f32_32x32x16_bf16 v[128:143], v[128:131], v[132:135], 0
	s_nop 7
	v_exp_f32_e32 v173, v144
	v_exp_f32_e32 v169, v145
	v_exp_f32_e32 v177, v146
	v_exp_f32_e32 v171, v147
	ds_read_b128 v[144:147], v227 offset:8192
	ds_read_b128 v[190:193], v228 offset:4096
	s_waitcnt lgkmcnt(2)
	v_mfma_f32_32x32x16_bf16 v[128:143], v[178:181], v[182:185], v[128:143]
	v_exp_f32_e32 v183, v148
	v_exp_f32_e32 v175, v149
	v_exp_f32_e32 v189, v150
	v_exp_f32_e32 v179, v151
	ds_read_b128 v[148:151], v230 offset:8192
	ds_read_b128 v[196:199], v232 offset:4096
	s_waitcnt lgkmcnt(2)
	v_mfma_f32_32x32x16_bf16 v[128:143], v[144:147], v[190:193], v[128:143]
	v_exp_f32_e32 v193, v152
	v_exp_f32_e32 v181, v153
	v_exp_f32_e32 v195, v154
	v_exp_f32_e32 v187, v155
	s_waitcnt lgkmcnt(0)
	v_mfma_f32_32x32x16_bf16 v[128:143], v[148:151], v[196:199], v[128:143]
	v_exp_f32_e32 v197, v156
	v_exp_f32_e32 v185, v157
	v_exp_f32_e32 v199, v158
	v_exp_f32_e32 v191, v159
	s_cmp_eq_u32 s4, 0x3f0000
	s_cbranch_scc1 .Lattn_nodma_a
	v_mov_b32_e32 v213, 0
	v_add_u32_e32 v212, s4, v202
	s_xor_b32 s8, s7, 0x4000
	v_lshl_add_u64 v[208:209], v[212:213], 1, s[66:67]
	s_add_i32 s9, s49, s8
	s_mov_b32 s10, m0
	s_mov_b32 m0, s9
	s_nop 0
	global_load_lds_dwordx4 v[208:209], off
	s_mov_b32 m0, s10
	v_add_u32_e32 v210, s4, v201
	v_lshl_add_u64 v[208:209], v[208:209], 0, s[38:39]
	s_add_i32 s9, s33, s8
	s_mov_b32 s10, m0
	s_mov_b32 m0, s9
	s_nop 0
	global_load_lds_dwordx4 v[208:209], off
	s_mov_b32 m0, s10
	v_add_u32_e32 v212, 0x10000, v210
	v_lshl_add_u64 v[208:209], v[212:213], 1, s[68:69]
	s_add_i32 s9, s54, s8
	s_mov_b32 s10, m0
	s_mov_b32 m0, s9
	s_nop 0
	global_load_lds_dwordx4 v[208:209], off
	s_mov_b32 m0, s10
	v_add_u32_e32 v212, 0x18000, v210
	v_lshl_add_u64 v[208:209], v[212:213], 1, s[68:69]
	s_add_i32 s8, s47, s8
	s_mov_b32 s9, m0
	s_mov_b32 m0, s8
	s_nop 0
	global_load_lds_dwordx4 v[208:209], off
	s_mov_b32 m0, s9
	s_branch .Lattn_dma_done_a

.Lattn_dma_done_a:
	v_exp_f32_e32 v172, v128
	v_exp_f32_e32 v170, v129
	v_exp_f32_e32 v176, v130
	v_exp_f32_e32 v168, v131
	v_exp_f32_e32 v182, v132
	v_exp_f32_e32 v178, v133
	v_exp_f32_e32 v188, v134
	v_exp_f32_e32 v174, v135
	v_exp_f32_e32 v192, v136
	v_exp_f32_e32 v186, v137
	v_exp_f32_e32 v194, v138
	v_exp_f32_e32 v180, v139
	v_exp_f32_e32 v196, v140
	v_exp_f32_e32 v190, v141
	v_exp_f32_e32 v198, v142
	v_exp_f32_e32 v184, v143
	v_cvt_pk_bf16_f32 v144, v173, v169
	v_cvt_pk_bf16_f32 v145, v177, v171
	v_cvt_pk_bf16_f32 v146, v183, v175
	v_cvt_pk_bf16_f32 v147, v189, v179
	v_cvt_pk_bf16_f32 v148, v193, v181
	v_cvt_pk_bf16_f32 v149, v195, v187
	v_cvt_pk_bf16_f32 v150, v197, v185
	v_cvt_pk_bf16_f32 v151, v199, v191
	v_cvt_pk_bf16_f32 v128, v172, v170
	v_cvt_pk_bf16_f32 v129, v176, v168
	v_cvt_pk_bf16_f32 v130, v182, v178
	v_cvt_pk_bf16_f32 v131, v188, v174
	v_cvt_pk_bf16_f32 v132, v192, v186
	v_cvt_pk_bf16_f32 v133, v194, v180
	v_cvt_pk_bf16_f32 v134, v196, v190
	v_cvt_pk_bf16_f32 v135, v198, v184
	v_add3_u32 v160, s7, v162, v160
	v_xad_u32 v252, v163, 64, s7
	v_add_u32_e32 v203, s7, v203
	v_add_u32_e32 v205, s7, v206
	ds_read_b64_tr_b16 v[136:137], v160 offset:32768
	ds_read_b64_tr_b16 v[138:139], v160 offset:34816
	ds_read_b64_tr_b16 v[140:141], v160 offset:36864
	ds_read_b64_tr_b16 v[142:143], v160 offset:38912
	ds_read_b64_tr_b16 v[152:153], v252 offset:32768
	ds_read_b64_tr_b16 v[154:155], v252 offset:34816
	ds_read_b64_tr_b16 v[156:157], v252 offset:36864
	ds_read_b64_tr_b16 v[158:159], v252 offset:38912
	ds_read_b64_tr_b16 v[208:209], v203 offset:32768
	ds_read_b64_tr_b16 v[210:211], v203 offset:34816
	ds_read_b64_tr_b16 v[212:213], v203 offset:36864
	ds_read_b64_tr_b16 v[214:215], v203 offset:38912
	ds_read_b64_tr_b16 v[216:217], v205 offset:32768
	ds_read_b64_tr_b16 v[218:219], v205 offset:34816
	ds_read_b64_tr_b16 v[220:221], v205 offset:36864
	ds_read_b64_tr_b16 v[222:223], v205 offset:38912
	s_waitcnt lgkmcnt(14)
	v_mfma_f32_32x32x16_bf16 v[64:79], v[144:147], v[136:139], v[64:79]
	v_mfma_f32_32x32x16_bf16 v[0:15], v[128:131], v[136:139], v[0:15]
	s_waitcnt lgkmcnt(10)
	v_mfma_f32_32x32x16_bf16 v[80:95], v[144:147], v[152:155], v[80:95]
	v_mfma_f32_32x32x16_bf16 v[16:31], v[128:131], v[152:155], v[16:31]
	s_waitcnt lgkmcnt(6)
	v_mfma_f32_32x32x16_bf16 v[96:111], v[144:147], v[208:211], v[96:111]
	v_mfma_f32_32x32x16_bf16 v[32:47], v[128:131], v[208:211], v[32:47]
	s_waitcnt lgkmcnt(2)
	v_mfma_f32_32x32x16_bf16 v[112:127], v[144:147], v[216:219], v[112:127]
	v_mfma_f32_32x32x16_bf16 v[48:63], v[128:131], v[216:219], v[48:63]
	v_mfma_f32_32x32x16_bf16 v[64:79], v[148:151], v[140:143], v[64:79]
	v_mfma_f32_32x32x16_bf16 v[0:15], v[132:135], v[140:143], v[0:15]
	v_mfma_f32_32x32x16_bf16 v[80:95], v[148:151], v[156:159], v[80:95]
	v_mfma_f32_32x32x16_bf16 v[16:31], v[132:135], v[156:159], v[16:31]
	v_mfma_f32_32x32x16_bf16 v[96:111], v[148:151], v[212:215], v[96:111]
	v_mfma_f32_32x32x16_bf16 v[32:47], v[132:135], v[212:215], v[32:47]
	s_waitcnt lgkmcnt(0)
	v_mfma_f32_32x32x16_bf16 v[112:127], v[148:151], v[220:223], v[112:127]
	v_mfma_f32_32x32x16_bf16 v[48:63], v[132:135], v[220:223], v[48:63]
	ds_read_b128 v[128:131], v207 offset:4096
	ds_read_b128 v[132:135], v224
	ds_read_b128 v[136:139], v225 offset:4096
	ds_read_b128 v[140:143], v226
	s_waitcnt lgkmcnt(2)
	v_mfma_f32_32x32x16_bf16 v[144:159], v[128:131], v[132:135], 0
	ds_read_b128 v[128:131], v227 offset:4096
	ds_read_b128 v[132:135], v228
	s_waitcnt lgkmcnt(2)
	v_mfma_f32_32x32x16_bf16 v[144:159], v[136:139], v[140:143], v[144:159]
	ds_read_b128 v[136:139], v230 offset:4096
	ds_read_b128 v[140:143], v232
	s_waitcnt lgkmcnt(2)
	v_mfma_f32_32x32x16_bf16 v[144:159], v[128:131], v[132:135], v[144:159]
	ds_read_b128 v[128:131], v207 offset:12288
	ds_read_b128 v[132:135], v224 offset:4096
	s_waitcnt lgkmcnt(2)
	v_mfma_f32_32x32x16_bf16 v[144:159], v[136:139], v[140:143], v[144:159]
	ds_read_b128 v[208:211], v225 offset:12288
	ds_read_b128 v[212:215], v226 offset:4096
	s_waitcnt lgkmcnt(2)
	v_mfma_f32_32x32x16_bf16 v[128:143], v[128:131], v[132:135], 0
	s_nop 7
	v_exp_f32_e32 v229, v144
	v_exp_f32_e32 v145, v145
	v_exp_f32_e32 v231, v146
	v_exp_f32_e32 v147, v147
	ds_read_b128 v[216:219], v227 offset:12288
	ds_read_b128 v[220:223], v228 offset:4096
	s_waitcnt lgkmcnt(2)
	v_mfma_f32_32x32x16_bf16 v[128:143], v[208:211], v[212:215], v[128:143]
	v_exp_f32_e32 v233, v148
	v_exp_f32_e32 v235, v149
	v_exp_f32_e32 v237, v150
	v_exp_f32_e32 v239, v151
	ds_read_b128 v[148:151], v230 offset:12288
	ds_read_b128 v[208:211], v232 offset:4096
	s_waitcnt lgkmcnt(2)
	v_mfma_f32_32x32x16_bf16 v[128:143], v[216:219], v[220:223], v[128:143]
	v_exp_f32_e32 v241, v152
	v_exp_f32_e32 v243, v153
	v_exp_f32_e32 v245, v154
	v_exp_f32_e32 v247, v155
	s_waitcnt lgkmcnt(0)
	v_mfma_f32_32x32x16_bf16 v[128:143], v[148:151], v[208:211], v[128:143]
	v_exp_f32_e32 v249, v156
	v_exp_f32_e32 v251, v157
	v_exp_f32_e32 v207, v158
	v_exp_f32_e32 v163, v159
	s_nop 7
	v_exp_f32_e32 v228, v128
	v_exp_f32_e32 v146, v129
	v_exp_f32_e32 v230, v130
	v_exp_f32_e32 v144, v131
	v_exp_f32_e32 v232, v132
	v_exp_f32_e32 v238, v133
	v_exp_f32_e32 v236, v134
	v_exp_f32_e32 v234, v135
	v_exp_f32_e32 v240, v136
	v_exp_f32_e32 v246, v137
	v_exp_f32_e32 v244, v138
	v_exp_f32_e32 v242, v139
	v_exp_f32_e32 v248, v140
	v_exp_f32_e32 v162, v141
	v_exp_f32_e32 v206, v142
	v_exp_f32_e32 v250, v143
	v_cvt_pk_bf16_f32 v148, v229, v145
	v_cvt_pk_bf16_f32 v149, v231, v147
	v_cvt_pk_bf16_f32 v150, v233, v235
	v_cvt_pk_bf16_f32 v151, v237, v239
	v_cvt_pk_bf16_f32 v152, v241, v243
	v_cvt_pk_bf16_f32 v153, v245, v247
	v_cvt_pk_bf16_f32 v154, v249, v251
	v_cvt_pk_bf16_f32 v155, v207, v163
	v_cvt_pk_bf16_f32 v128, v228, v146
	v_cvt_pk_bf16_f32 v129, v230, v144
	v_cvt_pk_bf16_f32 v130, v232, v238
	v_cvt_pk_bf16_f32 v131, v236, v234
	v_cvt_pk_bf16_f32 v132, v240, v246
	v_cvt_pk_bf16_f32 v133, v244, v242
	v_cvt_pk_bf16_f32 v134, v248, v162
	v_cvt_pk_bf16_f32 v135, v206, v250
	ds_read_b64_tr_b16 v[136:137], v160 offset:40960
	ds_read_b64_tr_b16 v[138:139], v160 offset:43008
	ds_read_b64_tr_b16 v[140:141], v160 offset:45056
	ds_read_b64_tr_b16 v[142:143], v160 offset:47104
	ds_read_b64_tr_b16 v[156:157], v252 offset:40960
	ds_read_b64_tr_b16 v[158:159], v252 offset:43008
	ds_read_b64_tr_b16 v[208:209], v252 offset:45056
	ds_read_b64_tr_b16 v[210:211], v252 offset:47104
	ds_read_b64_tr_b16 v[212:213], v203 offset:40960
	ds_read_b64_tr_b16 v[214:215], v203 offset:43008
	ds_read_b64_tr_b16 v[216:217], v203 offset:45056
	ds_read_b64_tr_b16 v[218:219], v203 offset:47104
	ds_read_b64_tr_b16 v[220:221], v205 offset:40960
	ds_read_b64_tr_b16 v[222:223], v205 offset:43008
	ds_read_b64_tr_b16 v[224:225], v205 offset:45056
	ds_read_b64_tr_b16 v[226:227], v205 offset:47104
	s_waitcnt lgkmcnt(14)
	v_mfma_f32_32x32x16_bf16 v[64:79], v[148:151], v[136:139], v[64:79]
	v_mfma_f32_32x32x16_bf16 v[0:15], v[128:131], v[136:139], v[0:15]
	s_waitcnt lgkmcnt(10)
	v_mfma_f32_32x32x16_bf16 v[80:95], v[148:151], v[156:159], v[80:95]
	v_mfma_f32_32x32x16_bf16 v[16:31], v[128:131], v[156:159], v[16:31]
	s_waitcnt lgkmcnt(6)
	v_mfma_f32_32x32x16_bf16 v[96:111], v[148:151], v[212:215], v[96:111]
	v_mfma_f32_32x32x16_bf16 v[32:47], v[128:131], v[212:215], v[32:47]
	s_waitcnt lgkmcnt(2)
	v_mfma_f32_32x32x16_bf16 v[112:127], v[148:151], v[220:223], v[112:127]
	v_mfma_f32_32x32x16_bf16 v[48:63], v[128:131], v[220:223], v[48:63]
	v_add_f32_e64 v128, v172, v176
	v_add_f32_e64 v129, v173, v177
	v_add_f32_e64 v130, v168, v170
	v_add_f32_e64 v131, v169, v171
	v_add_f32_e64 v128, v128, 0
	v_add_f32_e64 v129, v129, 0
	v_pk_add_f32 v[136:137], v[182:183], v[188:189]
	v_pk_add_f32 v[130:131], v[130:131], 0 op_sel_hi:[1,0]
	v_pk_add_f32 v[128:129], v[136:137], v[128:129]
	v_pk_add_f32 v[136:137], v[174:175], v[178:179]
	v_pk_add_f32 v[138:139], v[232:233], v[236:237]
	v_pk_add_f32 v[130:131], v[136:137], v[130:131]
	v_pk_add_f32 v[136:137], v[192:193], v[194:195]
	v_mfma_f32_32x32x16_bf16 v[64:79], v[152:155], v[140:143], v[64:79]
	v_add_f32_e64 v128, v136, v128
	v_add_f32_e64 v129, v137, v129
	v_add_f32_e64 v136, v180, v186
	v_add_f32_e64 v137, v181, v187
	v_add_f32_e64 v130, v136, v130
	v_add_f32_e64 v131, v137, v131
	v_pk_add_f32 v[136:137], v[196:197], v[198:199]
	s_nop 0
	v_pk_add_f32 v[128:129], v[136:137], v[128:129]
	v_pk_add_f32 v[136:137], v[184:185], v[190:191]
	v_mfma_f32_32x32x16_bf16 v[0:15], v[132:135], v[140:143], v[0:15]
	v_add_f32_e64 v130, v136, v130
	v_add_f32_e64 v131, v137, v131
	v_add_f32_e64 v136, v144, v146
	v_add_f32_e64 v137, v145, v147
	v_add_f32_e64 v128, v128, v130
	v_add_f32_e64 v129, v129, v131
	v_pk_add_f32 v[130:131], v[228:229], v[230:231]
	v_pk_add_f32 v[136:137], v[136:137], 0 op_sel_hi:[1,0]
	v_pk_add_f32 v[130:131], v[130:131], 0 op_sel_hi:[1,0]
	v_pk_add_f32 v[128:129], v[166:167], v[128:129]
	v_mfma_f32_32x32x16_bf16 v[80:95], v[152:155], v[208:211], v[80:95]
	v_add_f32_e64 v130, v138, v130
	v_add_f32_e64 v131, v139, v131
	v_add_f32_e64 v138, v234, v238
	v_add_f32_e64 v139, v235, v239
	v_add_f32_e64 v136, v138, v136
	v_add_f32_e64 v137, v139, v137
	v_pk_add_f32 v[138:139], v[240:241], v[244:245]
	s_nop 0
	v_pk_add_f32 v[130:131], v[138:139], v[130:131]
	v_mfma_f32_32x32x16_bf16 v[16:31], v[132:135], v[208:211], v[16:31]
	v_add_f32_e64 v138, v242, v246
	v_add_f32_e64 v139, v243, v247
	v_add_f32_e64 v136, v138, v136
	v_add_f32_e64 v137, v139, v137
	v_add_f32_e64 v138, v248, v206
	v_add_f32_e64 v139, v249, v207
	v_pk_add_f32 v[130:131], v[138:139], v[130:131]
	v_pk_add_f32 v[138:139], v[250:251], v[162:163]
	v_mfma_f32_32x32x16_bf16 v[96:111], v[152:155], v[216:219], v[96:111]
	v_add_f32_e64 v136, v138, v136
	v_add_f32_e64 v137, v139, v137
	v_add_f32_e64 v130, v130, v136
	v_add_f32_e64 v131, v131, v137
	v_add_f32_e64 v166, v128, v130
	v_add_f32_e64 v167, v129, v131
	v_mfma_f32_32x32x16_bf16 v[32:47], v[132:135], v[216:219], v[32:47]
	s_waitcnt lgkmcnt(0)
	v_mfma_f32_32x32x16_bf16 v[112:127], v[152:155], v[224:227], v[112:127]
	v_mfma_f32_32x32x16_bf16 v[48:63], v[132:135], v[224:227], v[48:63]
	s_waitcnt vmcnt(0)
	s_waitcnt lgkmcnt(0)
	s_addk_i32 s5, 0x4000
	s_add_i32 s4, s4, 0x10000
	s_and_b32 s7, s5, 0x4000
	s_cmp_eq_u32 s4, 0x400000
	s_cbranch_scc0 .Lattn_head_a
	s_barrier
